# attention: K(t+1) fragment reads issued in the previous ITER's last PV gaps instead of at the ITER head
# speedup vs baseline: 1.0094x; 1.0094x over previous
.Ltb_u1_b:
	s_ashr_i32 s11, s6, 6
	s_lshl_b32 s10, s43, 4
	s_lshl_b32 s26, s11, 2
	v_bfe_u32 v233, v237, 4, 2
	s_and_b32 s60, s10, 0xfffff000
	v_or_b32_e32 v52, s26, v233
	s_waitcnt vmcnt(0)
	v_add_u32_e32 v2, s60, v52
	v_ashrrev_i32_e32 v3, 31, v2
	v_readlane_b32 s18, v252, 31
	v_bitop3_b32 v0, s26, v237, v233 bitop3:0x36
	v_lshlrev_b64 v[2:3], 12, v[2:3]
	v_readlane_b32 s19, v252, 32
	s_and_b32 s46, s43, 15
	s_lshl_b32 s84, s28, 8
	v_lshl_add_u64 v[2:3], s[18:19], 0, v[2:3]
	v_lshlrev_b32_e32 v0, 4, v0
	s_xor_b32 s17, s46, 31
	s_and_b32 s2, s11, 3
	v_lshl_add_u64 v[2:3], v[2:3], 0, s[84:85]
	v_and_b32_e32 v0, 0xf0, v0
	s_lshl_b32 s27, s11, 3
	v_bfe_u32 v53, v237, 3, 3
	s_lshl_b32 s21, s17, 7
	s_lshl_b32 s22, s2, 5
	s_lshl_b32 s18, s28, 7
	v_lshl_add_u64 v[2:3], v[2:3], 0, v[0:1]
	v_or_b32_e32 v0, s27, v53
	s_or_b32 s20, s22, s21
	v_lshrrev_b32_e32 v54, 1, v0
	v_add_u32_e32 v4, s18, v0
	v_and_b32_e32 v235, 31, v237
	v_xor_b32_e32 v6, v54, v237
	v_ashrrev_i32_e32 v5, 31, v4
	v_readlane_b32 s36, v252, 39
	s_or_b32 s10, s20, s60
	v_lshlrev_b64 v[4:5], 15, v[4:5]
	v_readlane_b32 s37, v252, 40
	v_lshlrev_b32_e32 v0, 4, v6
	v_or_b32_e32 v6, s10, v235
	v_lshl_add_u64 v[4:5], s[36:37], 0, v[4:5]
	v_ashrrev_i32_e32 v7, 31, v6
	v_readlane_b32 s36, v252, 17
	s_ashr_i32 s3, s6, 8
	v_lshlrev_b64 v[6:7], 12, v[6:7]
	v_readlane_b32 s37, v252, 18
	s_ashr_i32 s61, s60, 31
	v_bfe_u32 v234, v237, 5, 1
	v_lshl_add_u64 v[6:7], s[36:37], 0, v[6:7]
	s_lshl_b32 s36, s3, 6
	v_lshl_add_u64 v[4:5], s[60:61], 1, v[4:5]
	v_and_b32_e32 v0, 0x70, v0
	v_lshl_add_u64 v[6:7], v[6:7], 0, s[84:85]
	s_ashr_i32 s37, s36, 31
	v_lshl_add_u64 v[4:5], v[4:5], 0, v[0:1]
	v_lshl_add_u64 v[6:7], s[36:37], 1, v[6:7]
	v_lshlrev_b32_e32 v0, 4, v234
	v_lshl_add_u64 v[6:7], v[6:7], 0, v[0:1]
	global_load_dwordx4 v[146:149], v[6:7], off nt
	global_load_dwordx4 v[150:153], v[6:7], off offset:32 nt
	global_load_dwordx4 v[154:157], v[6:7], off offset:64 nt
	global_load_dwordx4 v[158:161], v[6:7], off offset:96 nt
	s_lshl_b32 s11, s11, 10
	s_add_i32 s11, s11, 0
	s_mov_b32 m0, s11
	s_mov_b64 s[36:37], 0x20000
	global_load_lds_dwordx4 v[2:3], off
	v_lshl_add_u64 v[8:9], v[2:3], 0, s[36:37]
	s_add_i32 m0, s11, 0x2000
	s_mov_b64 s[36:37], 0x40000
	global_load_lds_dwordx4 v[8:9], off
	s_add_i32 m0, s11, 0x4000
	v_lshl_add_u64 v[8:9], v[2:3], 0, s[36:37]
	s_mov_b64 s[36:37], 0x60000
	global_load_lds_dwordx4 v[8:9], off
	v_lshl_add_u64 v[8:9], v[2:3], 0, s[36:37]
	s_add_i32 m0, s11, 0x6000
	s_mov_b64 s[36:37], 0x200000
	global_load_lds_dwordx4 v[8:9], off
	s_add_i32 m0, s11, 0xc000
	v_lshl_add_u64 v[8:9], v[4:5], 0, s[36:37]
	global_load_lds_dwordx4 v[4:5], off
	s_add_i32 m0, s11, 0xe000
	s_mov_b64 s[36:37], 0xa0000
	global_load_lds_dwordx4 v[8:9], off
	s_add_i32 m0, s11, 0x8000
	v_lshl_add_u64 v[8:9], v[2:3], 0, s[34:35]
	global_load_lds_dwordx4 v[8:9], off
	v_lshl_add_u64 v[2:3], v[2:3], 0, s[36:37]
	s_add_i32 m0, s11, 0xa000
	s_mov_b64 s[36:37], 0x80
	global_load_lds_dwordx4 v[2:3], off
	s_add_i32 m0, s11, 0x10000
	v_lshl_add_u64 v[2:3], v[4:5], 0, s[36:37]
	s_mov_b64 s[36:37], 0x200080
	global_load_lds_dwordx4 v[2:3], off
	v_lshl_add_u64 v[2:3], v[4:5], 0, s[36:37]
	s_add_i32 m0, s11, 0x12000
	v_and_b32_e32 v0, 19, v237
	global_load_lds_dwordx4 v[2:3], off
	v_lshlrev_b32_e32 v2, 1, v237
	v_lshrrev_b32_e32 v35, 1, v34
	v_and_or_b32 v0, v2, 8, v0
	v_and_b32_e32 v22, 4, v35
	v_or_b32_e32 v2, v0, v22
	v_lshl_or_b32 v45, s3, 3, v234
	v_lshlrev_b32_e32 v44, 8, v2
	v_bitop3_b32 v2, v2, v45, 15 bitop3:0x6c
	v_lshl_add_u32 v239, v2, 4, v44
	s_waitcnt vmcnt(4)
	s_barrier
	v_add_u32_e32 v6, 0, v239
	v_bitop3_b32 v0, v0, 15, v22 bitop3:0xc8
	ds_read_b128 v[2:5], v6
	ds_read_b128 v[18:21], v6 offset:8192
	v_bitop3_b32 v22, v45, v0, 2 bitop3:0x36
	v_lshl_add_u32 v240, v22, 4, v44
	v_add_u32_e32 v40, 0, v240
	ds_read_b128 v[36:39], v40
	s_waitcnt vmcnt(0) lgkmcnt(0)
	v_mfma_f32_32x32x16_bf16 v[2:17], v[2:5], v[146:149], 0
	ds_read_b128 v[40:43], v40 offset:8192
	v_bfe_u32 v34, v34, 1, 3
	v_bitop3_b32 v57, v234, v34, 2 bitop3:0x36
	v_bitop3_b32 v58, v234, v34, 4 bitop3:0x36
	v_bitop3_b32 v59, v234, v34, 6 bitop3:0x36
	s_and_b32 s56, s42, 0xfffff000
	s_add_i32 s26, s26, s56
	v_mfma_f32_32x32x16_bf16 v[18:33], v[18:21], v[146:149], 0
	s_lshr_b32 s16, s43, 4
	s_and_b32 s16, s16, 15
	s_lshl_b32 s36, s16, 7
	s_lshl_b32 s37, s16, 8
	s_add_i32 s27, s27, s36
	s_ashr_i32 s57, s56, 31
	s_lshl_b64 s[44:45], s[56:57], 1
	v_mfma_f32_32x32x16_bf16 v[2:17], v[36:39], v[150:153], v[2:17]
	v_bitop3_b32 v36, v45, v0, 4 bitop3:0x36
	v_lshl_add_u32 v241, v36, 4, v44
	v_add_u32_e32 v46, 0, v241
	ds_read_b128 v[36:39], v46
	v_bitop3_b32 v0, v45, v0, 6 bitop3:0x36
	v_lshl_add_u32 v243, v0, 4, v44
	v_add_u32_e32 v0, 0, v243
	s_waitcnt lgkmcnt(1)
	v_mfma_f32_32x32x16_bf16 v[18:33], v[40:43], v[150:153], v[18:33]
	ds_read_b128 v[40:43], v46 offset:8192
	v_lshlrev_b32_e32 v236, 3, v234
	s_mov_b32 s84, s85
	v_bitop3_b32 v56, v35, v234, 7 bitop3:0x6c
	s_mov_b32 s86, s85
	s_mov_b32 s87, s85
	s_mov_b32 s88, s85
	s_waitcnt lgkmcnt(1)
	v_mfma_f32_32x32x16_bf16 v[2:17], v[36:39], v[154:157], v[2:17]
	ds_read_b128 v[36:39], v0
	s_mov_b32 s89, s85
	s_mov_b32 s90, s85
	s_mov_b32 s91, s85
	s_mov_b32 s92, s85
	s_mov_b32 s93, s85
	s_mov_b32 s94, s85
	s_waitcnt lgkmcnt(1)
	v_mfma_f32_32x32x16_bf16 v[18:33], v[40:43], v[154:157], v[18:33]
	ds_read_b128 v[40:43], v0 offset:8192
	s_mov_b32 s95, s85
	s_mov_b32 s96, s85
	s_mov_b32 s97, s85
	s_mov_b32 s98, s85
	s_mov_b32 s99, s85
	s_lshl_b32 s16, s17, 1
	s_waitcnt lgkmcnt(1)
	v_mfma_f32_32x32x16_bf16 v[2:17], v[36:39], v[158:161], v[2:17]
	v_lshlrev_b32_e32 v55, 7, v235
	s_lshr_b32 s19, s20, 6
	s_add_i32 s17, s16, 2
	s_add_i32 s19, s19, 1
	v_lshl_or_b32 v244, v56, 4, v55
	v_lshl_or_b32 v245, v57, 4, v55
	v_lshl_or_b32 v246, v58, 4, v55
	s_waitcnt lgkmcnt(0)
	v_mfma_f32_32x32x16_bf16 v[18:33], v[40:43], v[158:161], v[18:33]
	s_nop 2
	v_max_f32_e32 v34, v3, v3
	v_lshl_or_b32 v247, v59, 4, v55
	s_mov_b32 s23, 1
	v_and_b32_e32 v238, 63, v237
	s_mov_b32 s31, 0x8000
	s_min_u32 s19, s17, s19
	s_addk_i32 s20, 0xff50
	s_nop 1
	v_max_f32_e32 v0, v19, v19
	v_max_f32_e32 v0, v34, v0
	v_max3_f32 v0, v2, v18, v0
	v_max3_f32 v34, v20, v5, v21
	v_max3_f32 v0, v0, v4, v34
	v_max3_f32 v34, v22, v7, v23
	v_max3_f32 v0, v0, v6, v34
	v_max3_f32 v34, v24, v9, v25
	v_max3_f32 v0, v0, v8, v34
	v_max3_f32 v34, v26, v11, v27
	v_max3_f32 v0, v0, v10, v34
	v_max3_f32 v34, v28, v13, v29
	v_max3_f32 v0, v0, v12, v34
	v_max3_f32 v34, v30, v15, v31
	v_max3_f32 v0, v0, v14, v34
	v_max3_f32 v34, v32, v17, v33
	v_max3_f32 v0, v0, v16, v34
	v_mov_b32_e32 v34, v0
	s_nop 1
	v_permlane32_swap_b32_e32 v0, v34
	v_max_f32_e32 v34, v34, v34
	v_max_f32_e32 v0, v0, v0
	v_max_f32_e32 v213, v0, v34
	v_sub_f32_e32 v0, v2, v213
	v_exp_f32_e32 v60, v0
	v_sub_f32_e32 v0, v18, v213
	v_exp_f32_e32 v61, v0
	v_sub_f32_e32 v0, v3, v213
	v_sub_f32_e32 v2, v19, v213
	v_exp_f32_e32 v0, v0
	v_exp_f32_e32 v2, v2
	v_add_f32_e32 v3, v61, v60
	v_mov_b64_e32 v[34:35], s[84:85]
	v_cvt_pk_bf16_f32 v162, v60, v0
	v_pk_add_f32 v[18:19], v[2:3], v[0:1]
	v_sub_f32_e32 v3, v4, v213
	v_sub_f32_e32 v4, v20, v213
	v_pk_add_f32 v[18:19], v[18:19], v[18:19] op_sel_hi:[0,1]
	v_exp_f32_e32 v62, v4
	v_sub_f32_e32 v4, v5, v213
	v_exp_f32_e32 v3, v3
	v_exp_f32_e32 v18, v4
	v_sub_f32_e32 v4, v21, v213
	v_exp_f32_e32 v4, v4
	v_add_f32_e32 v5, v62, v3
	v_sub_u32_e32 v0, 7, v237
	v_cvt_pk_bf16_f32 v178, v61, v2
	v_pk_add_f32 v[20:21], v[4:5], v[18:19]
	v_sub_f32_e32 v5, v6, v213
	v_sub_f32_e32 v6, v22, v213
	v_pk_add_f32 v[20:21], v[20:21], v[20:21] op_sel_hi:[0,1]
	v_exp_f32_e32 v19, v6
	v_sub_f32_e32 v6, v7, v213
	v_exp_f32_e32 v5, v5
	v_exp_f32_e32 v20, v6
	v_sub_f32_e32 v6, v23, v213
	v_exp_f32_e32 v6, v6
	v_add_f32_e32 v7, v19, v5
	v_and_b32_e32 v0, 3, v0
	v_mov_b32_e32 v2, s33
	v_pk_add_f32 v[22:23], v[6:7], v[20:21]
	v_sub_f32_e32 v7, v8, v213
	v_sub_f32_e32 v8, v24, v213
	v_pk_add_f32 v[22:23], v[22:23], v[22:23] op_sel_hi:[0,1]
	v_exp_f32_e32 v21, v8
	v_sub_f32_e32 v8, v9, v213
	v_exp_f32_e32 v7, v7
	v_exp_f32_e32 v22, v8
	v_sub_f32_e32 v8, v25, v213
	v_exp_f32_e32 v8, v8
	v_add_f32_e32 v9, v21, v7
	s_movk_i32 s33, 0x510
	v_mad_u32_u24 v0, v0, s33, v2
	v_pk_add_f32 v[24:25], v[8:9], v[22:23]
	v_sub_f32_e32 v9, v10, v213
	v_sub_f32_e32 v10, v26, v213
	v_pk_add_f32 v[24:25], v[24:25], v[24:25] op_sel_hi:[0,1]
	v_exp_f32_e32 v23, v10
	v_sub_f32_e32 v10, v11, v213
	v_exp_f32_e32 v9, v9
	v_exp_f32_e32 v24, v10
	v_sub_f32_e32 v10, v27, v213
	v_exp_f32_e32 v10, v10
	v_add_f32_e32 v11, v23, v9
	v_or_b32_e32 v2, s26, v233
	v_cvt_pk_bf16_f32 v163, v3, v18
	v_pk_add_f32 v[26:27], v[10:11], v[24:25]
	v_sub_f32_e32 v11, v12, v213
	v_sub_f32_e32 v12, v28, v213
	v_pk_add_f32 v[26:27], v[26:27], v[26:27] op_sel_hi:[0,1]
	v_exp_f32_e32 v25, v12
	v_sub_f32_e32 v12, v13, v213
	v_exp_f32_e32 v11, v11
	v_exp_f32_e32 v26, v12
	v_sub_f32_e32 v12, v29, v213
	v_exp_f32_e32 v12, v12
	v_add_f32_e32 v13, v25, v11
	v_ashrrev_i32_e32 v3, 31, v2
	v_lshlrev_b64 v[214:215], 12, v[2:3]
	v_pk_add_f32 v[28:29], v[12:13], v[26:27]
	v_sub_f32_e32 v13, v14, v213
	v_sub_f32_e32 v14, v30, v213
	v_pk_add_f32 v[28:29], v[28:29], v[28:29] op_sel_hi:[0,1]
	v_exp_f32_e32 v27, v14
	v_sub_f32_e32 v14, v15, v213
	v_exp_f32_e32 v13, v13
	v_exp_f32_e32 v28, v14
	v_sub_f32_e32 v14, v31, v213
	v_exp_f32_e32 v14, v14
	v_sub_f32_e32 v15, v16, v213
	v_exp_f32_e32 v63, v15
	v_sub_f32_e32 v15, v32, v213
	v_exp_f32_e32 v32, v15
	v_add_f32_e32 v15, v27, v13
	v_pk_add_f32 v[30:31], v[14:15], v[28:29]
	v_bitop3_b32 v2, v52, 15, v237 bitop3:0x48
	v_pk_add_f32 v[30:31], v[30:31], v[30:31] op_sel_hi:[0,1]
	v_sub_f32_e32 v15, v17, v213
	v_lshlrev_b32_e32 v2, 4, v2
	v_exp_f32_e32 v30, v15
	v_sub_f32_e32 v15, v33, v213
	v_or3_b32 v214, v214, s37, v2
	v_or_b32_e32 v2, s27, v53
	v_exp_f32_e32 v50, v15
	v_ashrrev_i32_e32 v3, 31, v2
	v_cvt_pk_bf16_f32 v179, v62, v4
	v_lshlrev_b64 v[2:3], 15, v[2:3]
	v_bitop3_b32 v4, v54, 7, v237 bitop3:0x48
	v_lshl_or_b32 v2, v4, 4, v2
	v_add_f32_e32 v51, v32, v63
	v_lshl_add_u64 v[216:217], v[2:3], 0, s[44:45]
	v_sub_u32_e32 v2, v236, v235
	v_mov_b64_e32 v[48:49], s[98:99]
	v_pk_add_f32 v[16:17], v[50:51], v[30:31]
	v_subrev_u32_e32 v2, s22, v2
	v_mov_b64_e32 v[36:37], s[86:87]
	v_mov_b64_e32 v[38:39], s[88:89]
	v_mov_b64_e32 v[40:41], s[90:91]
	v_mov_b64_e32 v[42:43], s[92:93]
	v_mov_b64_e32 v[44:45], s[94:95]
	v_mov_b64_e32 v[46:47], s[96:97]
	v_xor_b32_e32 v66, 0x80000000, v213
	v_add_f32_e32 v242, v16, v17
	v_cvt_pk_bf16_f32 v164, v5, v20
	v_cvt_pk_bf16_f32 v165, v7, v22
	v_cvt_pk_bf16_f32 v170, v9, v24
	v_cvt_pk_bf16_f32 v171, v11, v26
	v_cvt_pk_bf16_f32 v172, v13, v28
	v_cvt_pk_bf16_f32 v173, v63, v30
	v_cvt_pk_bf16_f32 v180, v19, v6
	v_cvt_pk_bf16_f32 v181, v21, v8
	v_cvt_pk_bf16_f32 v186, v23, v10
	v_cvt_pk_bf16_f32 v187, v25, v12
	v_cvt_pk_bf16_f32 v188, v27, v14
	v_cvt_pk_bf16_f32 v189, v32, v50
	v_subrev_u32_e32 v248, s21, v2
	v_mov_b64_e32 v[64:65], v[48:49]
	v_mov_b64_e32 v[18:19], v[34:35]
	v_mov_b64_e32 v[2:3], v[34:35]
	v_readlane_b32 s94, v255, 10
	v_readlane_b32 s90, v255, 12
	v_mov_b32_e32 v67, v66
	v_mov_b32_e32 v68, v66
	v_mov_b32_e32 v69, v66
	v_mov_b32_e32 v70, v66
	v_mov_b32_e32 v71, v66
	v_mov_b32_e32 v72, v66
	v_mov_b32_e32 v73, v66
	v_mov_b32_e32 v74, v66
	v_mov_b32_e32 v75, v66
	v_mov_b32_e32 v76, v66
	v_mov_b32_e32 v77, v66
	v_mov_b32_e32 v78, v66
	v_mov_b32_e32 v79, v66
	v_mov_b32_e32 v80, v66
	v_mov_b32_e32 v81, v66
	s_mov_b32 s21, 0
	v_mov_b32_e32 v166, 0
	v_mov_b32_e32 v167, 0
	v_mov_b32_e32 v168, 0
	v_mov_b32_e32 v169, 0
	v_mov_b32_e32 v174, 0
	v_mov_b32_e32 v175, 0
	v_mov_b32_e32 v176, 0
	v_mov_b32_e32 v177, 0
	v_mov_b32_e32 v182, 0
	v_mov_b32_e32 v183, 0
	v_mov_b32_e32 v184, 0
	v_mov_b32_e32 v185, 0
	v_mov_b32_e32 v190, 0
	v_mov_b32_e32 v191, 0
	v_mov_b32_e32 v192, 0
	v_mov_b32_e32 v193, 0
	v_mov_b64_e32 v[62:63], v[46:47]
	v_mov_b64_e32 v[60:61], v[44:45]
	v_mov_b64_e32 v[58:59], v[42:43]
	v_mov_b64_e32 v[56:57], v[40:41]
	v_mov_b64_e32 v[54:55], v[38:39]
	v_mov_b64_e32 v[52:53], v[36:37]
	v_mov_b64_e32 v[50:51], v[34:35]
	v_mov_b64_e32 v[20:21], v[36:37]
	v_mov_b64_e32 v[22:23], v[38:39]
	v_mov_b64_e32 v[24:25], v[40:41]
	v_mov_b64_e32 v[26:27], v[42:43]
	v_mov_b64_e32 v[28:29], v[44:45]
	v_mov_b64_e32 v[30:31], v[46:47]
	v_mov_b64_e32 v[32:33], v[48:49]
	v_mov_b64_e32 v[4:5], v[36:37]
	v_mov_b64_e32 v[6:7], v[38:39]
	v_mov_b64_e32 v[8:9], v[40:41]
	v_mov_b64_e32 v[10:11], v[42:43]
	v_mov_b64_e32 v[12:13], v[44:45]
	v_mov_b64_e32 v[14:15], v[46:47]
	v_mov_b64_e32 v[16:17], v[48:49]
	s_mov_b32 s33, 0x4000
	s_mov_b32 s48, 0
	s_mov_b32 s49, 0
	s_movk_i32 s92, 0x6e
	s_movk_i32 s93, 0xd0
	s_mov_b32 s57, 0x41000000
	v_readlane_b32 s95, v255, 11
	v_readlane_b32 s91, v255, 13
	s_add_u32 s80, s8, 0xd0c0000
	s_addc_u32 s81, s9, 0
	s_add_u32 s62, s8, 0xd0e0000
	s_addc_u32 s63, s9, 0
	s_add_u32 s96, s8, 0x15000100
	s_addc_u32 s97, s9, 0
	s_add_u32 s58, s8, 0x15200100
	s_addc_u32 s59, s9, 0
	s_add_u32 s50, s8, 0xd100000
	s_addc_u32 s51, s9, 0
	s_add_u32 s4, s8, 0xd120000
	s_addc_u32 s5, s9, 0
	s_add_u32 s0, s8, 0x15000180
	s_addc_u32 s1, s9, 0
	s_add_u32 s52, s8, 0x15200180
	s_addc_u32 s53, s9, 0
	v_add_u32_e32 v244, 0x8000, v244
	v_add_u32_e32 v245, 0x8000, v245
	v_add_u32_e32 v246, 0x8000, v246
	v_add_u32_e32 v247, 0x8000, v247
	ds_read_b128 v[202:205], v239 offset:16384
	ds_read_b128 v[194:197], v239 offset:24576
	ds_read_b128 v[198:201], v240 offset:16384

.LBB0_168:
	s_barrier

.LBB0_185:
	ds_read_b128 v[126:129], v244 offset:16384
	s_waitcnt lgkmcnt(1)
	v_mfma_f32_32x32x16_bf16 v[82:97], v[202:205], v[146:149], v[66:81]
	ds_read_b128 v[122:125], v240 offset:24576
	v_mfma_f32_32x32x16_bf16 v[98:113], v[194:197], v[146:149], v[66:81]
	ds_read_b128 v[114:117], v241 offset:16384
	v_mfma_f32_32x32x16_bf16 v[82:97], v[198:201], v[150:153], v[82:97]
	ds_read_b128 v[118:121], v241 offset:24576
	s_waitcnt lgkmcnt(0)
	v_mfma_f32_32x32x16_bf16 v[98:113], v[122:125], v[150:153], v[98:113]
	ds_read_b128 v[122:125], v243 offset:16384
	v_mfma_f32_32x32x16_bf16 v[82:97], v[114:117], v[154:157], v[82:97]
	ds_read_b128 v[114:117], v243 offset:24576
	v_mfma_f32_32x32x16_bf16 v[98:113], v[118:121], v[154:157], v[98:113]
	s_waitcnt lgkmcnt(0)
	v_mfma_f32_32x32x16_bf16 v[82:97], v[122:125], v[158:161], v[82:97]
	v_mfma_f32_32x32x16_bf16 v[98:113], v[114:117], v[158:161], v[98:113]
	s_nop 0
	ds_read_b128 v[122:125], v244 offset:20480
	ds_read_b128 v[118:121], v244 offset:24576
	ds_read_b128 v[114:117], v244 offset:28672
	s_add_i32 s22, s21, 64
	s_cmp_le_u32 s22, s20
	s_cbranch_scc0 .Lnear_u1e

.LBB0_196:
	s_waitcnt lgkmcnt(0)
	ds_read_b128 v[202:205], v239 offset:32768
	ds_read_b128 v[194:197], v239 offset:40960
	ds_read_b128 v[198:201], v240 offset:32768
	v_mfma_f32_32x32x16_bf16 v[18:33], v[118:121], v[186:189], v[18:33]
	v_exp_f32_e32 v118, v110
	v_exp_f32_e32 v119, v111
	v_add_f32_e32 v120, v122, v118
	v_add_f32_e32 v121, v123, v119
	v_cvt_pk_bf16_f32 v192, v118, v119
	v_mfma_f32_32x32x16_bf16 v[2:17], v[114:117], v[186:189], v[2:17]
	v_exp_f32_e32 v114, v112
	v_exp_f32_e32 v115, v113
	v_add_f32_e32 v116, v120, v114
	v_add_f32_e32 v117, v121, v115
	v_cvt_pk_bf16_f32 v193, v114, v115
	v_add_f32_e32 v212, v116, v117
	v_cmp_nge_f32_e32 vcc, s7, v212
	s_cbranch_vccnz .Lrare_u1e

.LBB0_225:
	ds_read_b128 v[126:129], v244 offset:32768
	s_waitcnt lgkmcnt(1)
	v_mfma_f32_32x32x16_bf16 v[82:97], v[202:205], v[146:149], v[66:81]
	ds_read_b128 v[122:125], v240 offset:40960
	v_mfma_f32_32x32x16_bf16 v[98:113], v[194:197], v[146:149], v[66:81]
	ds_read_b128 v[114:117], v241 offset:32768
	v_mfma_f32_32x32x16_bf16 v[82:97], v[198:201], v[150:153], v[82:97]
	ds_read_b128 v[118:121], v241 offset:40960
	s_waitcnt lgkmcnt(0)
	v_mfma_f32_32x32x16_bf16 v[98:113], v[122:125], v[150:153], v[98:113]
	ds_read_b128 v[122:125], v243 offset:32768
	v_mfma_f32_32x32x16_bf16 v[82:97], v[114:117], v[154:157], v[82:97]
	ds_read_b128 v[114:117], v243 offset:40960
	v_mfma_f32_32x32x16_bf16 v[98:113], v[118:121], v[154:157], v[98:113]
	s_waitcnt lgkmcnt(0)
	v_mfma_f32_32x32x16_bf16 v[82:97], v[122:125], v[158:161], v[82:97]
	v_mfma_f32_32x32x16_bf16 v[98:113], v[114:117], v[158:161], v[98:113]
	s_nop 0
	ds_read_b128 v[122:125], v244 offset:36864
	ds_read_b128 v[118:121], v244 offset:40960
	ds_read_b128 v[114:117], v244 offset:45056
	s_add_i32 s26, s21, 0x80
	s_cmp_le_u32 s26, s20
	s_cbranch_scc0 .Lnear_u1o

.LBB0_236:
	s_waitcnt lgkmcnt(0)
	ds_read_b128 v[202:205], v239
	ds_read_b128 v[194:197], v239 offset:8192
	ds_read_b128 v[198:201], v240
	v_mfma_f32_32x32x16_bf16 v[18:33], v[118:121], v[190:193], v[18:33]
	v_exp_f32_e32 v118, v110
	v_exp_f32_e32 v119, v111
	v_add_f32_e32 v120, v122, v118
	v_add_f32_e32 v121, v123, v119
	v_cvt_pk_bf16_f32 v188, v118, v119
	v_mfma_f32_32x32x16_bf16 v[2:17], v[114:117], v[190:193], v[2:17]
	v_exp_f32_e32 v114, v112
	v_exp_f32_e32 v115, v113
	v_add_f32_e32 v116, v120, v114
	v_add_f32_e32 v117, v121, v115
	v_cvt_pk_bf16_f32 v189, v114, v115
	v_add_f32_e32 v212, v116, v117
	v_cmp_nge_f32_e32 vcc, s7, v212
	s_cbranch_vccnz .Lrare_u1o

.Lr1u1_LBB0_185:
	ds_read_b128 v[126:129], v244 offset:49152
	s_waitcnt lgkmcnt(1)
	v_mfma_f32_32x32x16_bf16 v[82:97], v[202:205], v[146:149], v[66:81]
	ds_read_b128 v[122:125], v240 offset:8192
	v_mfma_f32_32x32x16_bf16 v[98:113], v[194:197], v[146:149], v[66:81]
	ds_read_b128 v[114:117], v241
	v_mfma_f32_32x32x16_bf16 v[82:97], v[198:201], v[150:153], v[82:97]
	ds_read_b128 v[118:121], v241 offset:8192
	s_waitcnt lgkmcnt(0)
	v_mfma_f32_32x32x16_bf16 v[98:113], v[122:125], v[150:153], v[98:113]
	ds_read_b128 v[122:125], v243
	v_mfma_f32_32x32x16_bf16 v[82:97], v[114:117], v[154:157], v[82:97]
	ds_read_b128 v[114:117], v243 offset:8192
	v_mfma_f32_32x32x16_bf16 v[98:113], v[118:121], v[154:157], v[98:113]
	s_waitcnt lgkmcnt(0)
	v_mfma_f32_32x32x16_bf16 v[82:97], v[122:125], v[158:161], v[82:97]
	v_mfma_f32_32x32x16_bf16 v[98:113], v[114:117], v[158:161], v[98:113]
	s_nop 0
	ds_read_b128 v[122:125], v244 offset:53248
	ds_read_b128 v[118:121], v244 offset:57344
	ds_read_b128 v[114:117], v244 offset:61440
	s_add_i32 s22, s21, 64
	s_cmp_le_u32 s22, s20
	s_cbranch_scc0 .Lr1u1_Lnear_u1e

.Lr1u1_LBB0_196:
	s_waitcnt lgkmcnt(0)
	ds_read_b128 v[202:205], v239 offset:16384
	ds_read_b128 v[194:197], v239 offset:24576
	ds_read_b128 v[198:201], v240 offset:16384
	v_mfma_f32_32x32x16_bf16 v[18:33], v[118:121], v[186:189], v[18:33]
	v_exp_f32_e32 v118, v110
	v_exp_f32_e32 v119, v111
	v_add_f32_e32 v120, v122, v118
	v_add_f32_e32 v121, v123, v119
	v_cvt_pk_bf16_f32 v192, v118, v119
	v_mfma_f32_32x32x16_bf16 v[2:17], v[114:117], v[186:189], v[2:17]
	v_exp_f32_e32 v114, v112
	v_exp_f32_e32 v115, v113
	v_add_f32_e32 v116, v120, v114
	v_add_f32_e32 v117, v121, v115
	v_cvt_pk_bf16_f32 v193, v114, v115
	v_add_f32_e32 v212, v116, v117
	v_cmp_nge_f32_e32 vcc, s7, v212
	s_cbranch_vccnz .Lr1u1_Lrare_u1e

.Lr1u1_LBB0_225:
	ds_read_b128 v[126:129], v244 offset:16384
	s_waitcnt lgkmcnt(1)
	v_mfma_f32_32x32x16_bf16 v[82:97], v[202:205], v[146:149], v[66:81]
	ds_read_b128 v[122:125], v240 offset:24576
	v_mfma_f32_32x32x16_bf16 v[98:113], v[194:197], v[146:149], v[66:81]
	ds_read_b128 v[114:117], v241 offset:16384
	v_mfma_f32_32x32x16_bf16 v[82:97], v[198:201], v[150:153], v[82:97]
	ds_read_b128 v[118:121], v241 offset:24576
	s_waitcnt lgkmcnt(0)
	v_mfma_f32_32x32x16_bf16 v[98:113], v[122:125], v[150:153], v[98:113]
	ds_read_b128 v[122:125], v243 offset:16384
	v_mfma_f32_32x32x16_bf16 v[82:97], v[114:117], v[154:157], v[82:97]
	ds_read_b128 v[114:117], v243 offset:24576
	v_mfma_f32_32x32x16_bf16 v[98:113], v[118:121], v[154:157], v[98:113]
	s_waitcnt lgkmcnt(0)
	v_mfma_f32_32x32x16_bf16 v[82:97], v[122:125], v[158:161], v[82:97]
	v_mfma_f32_32x32x16_bf16 v[98:113], v[114:117], v[158:161], v[98:113]
	s_nop 0
	ds_read_b128 v[122:125], v244 offset:20480
	ds_read_b128 v[118:121], v244 offset:24576
	ds_read_b128 v[114:117], v244 offset:28672
	s_add_i32 s26, s21, 0x80
	s_cmp_le_u32 s26, s20
	s_cbranch_scc0 .Lr1u1_Lnear_u1o

.Lr1u1_LBB0_236:
	s_waitcnt lgkmcnt(0)
	ds_read_b128 v[202:205], v239 offset:32768
	ds_read_b128 v[194:197], v239 offset:40960
	ds_read_b128 v[198:201], v240 offset:32768
	v_mfma_f32_32x32x16_bf16 v[18:33], v[118:121], v[190:193], v[18:33]
	v_exp_f32_e32 v118, v110
	v_exp_f32_e32 v119, v111
	v_add_f32_e32 v120, v122, v118
	v_add_f32_e32 v121, v123, v119
	v_cvt_pk_bf16_f32 v188, v118, v119
	v_mfma_f32_32x32x16_bf16 v[2:17], v[114:117], v[190:193], v[2:17]
	v_exp_f32_e32 v114, v112
	v_exp_f32_e32 v115, v113
	v_add_f32_e32 v116, v120, v114
	v_add_f32_e32 v117, v121, v115
	v_cvt_pk_bf16_f32 v189, v114, v115
	v_add_f32_e32 v212, v116, v117
	v_cmp_nge_f32_e32 vcc, s7, v212
	s_cbranch_vccnz .Lr1u1_Lrare_u1o

.Lr2u1_LBB0_185:
	ds_read_b128 v[126:129], v244 offset:32768
	s_waitcnt lgkmcnt(1)
	v_mfma_f32_32x32x16_bf16 v[82:97], v[202:205], v[146:149], v[66:81]
	ds_read_b128 v[122:125], v240 offset:40960
	v_mfma_f32_32x32x16_bf16 v[98:113], v[194:197], v[146:149], v[66:81]
	ds_read_b128 v[114:117], v241 offset:32768
	v_mfma_f32_32x32x16_bf16 v[82:97], v[198:201], v[150:153], v[82:97]
	ds_read_b128 v[118:121], v241 offset:40960
	s_waitcnt lgkmcnt(0)
	v_mfma_f32_32x32x16_bf16 v[98:113], v[122:125], v[150:153], v[98:113]
	ds_read_b128 v[122:125], v243 offset:32768
	v_mfma_f32_32x32x16_bf16 v[82:97], v[114:117], v[154:157], v[82:97]
	ds_read_b128 v[114:117], v243 offset:40960
	v_mfma_f32_32x32x16_bf16 v[98:113], v[118:121], v[154:157], v[98:113]
	s_waitcnt lgkmcnt(0)
	v_mfma_f32_32x32x16_bf16 v[82:97], v[122:125], v[158:161], v[82:97]
	v_mfma_f32_32x32x16_bf16 v[98:113], v[114:117], v[158:161], v[98:113]
	s_nop 0
	ds_read_b128 v[122:125], v244 offset:36864
	ds_read_b128 v[118:121], v244 offset:40960
	ds_read_b128 v[114:117], v244 offset:45056
	s_add_i32 s22, s21, 64
	s_cmp_le_u32 s22, s20
	s_cbranch_scc0 .Lr2u1_Lnear_u1e

.Lr2u1_LBB0_196:
	s_waitcnt lgkmcnt(0)
	ds_read_b128 v[202:205], v239
	ds_read_b128 v[194:197], v239 offset:8192
	ds_read_b128 v[198:201], v240
	v_mfma_f32_32x32x16_bf16 v[18:33], v[118:121], v[186:189], v[18:33]
	v_exp_f32_e32 v118, v110
	v_exp_f32_e32 v119, v111
	v_add_f32_e32 v120, v122, v118
	v_add_f32_e32 v121, v123, v119
	v_cvt_pk_bf16_f32 v192, v118, v119
	v_mfma_f32_32x32x16_bf16 v[2:17], v[114:117], v[186:189], v[2:17]
	v_exp_f32_e32 v114, v112
	v_exp_f32_e32 v115, v113
	v_add_f32_e32 v116, v120, v114
	v_add_f32_e32 v117, v121, v115
	v_cvt_pk_bf16_f32 v193, v114, v115
	v_add_f32_e32 v212, v116, v117
	v_cmp_nge_f32_e32 vcc, s7, v212
	s_cbranch_vccnz .Lr2u1_Lrare_u1e

.Lr2u1_LBB0_225:
	ds_read_b128 v[126:129], v244 offset:49152
	s_waitcnt lgkmcnt(1)
	v_mfma_f32_32x32x16_bf16 v[82:97], v[202:205], v[146:149], v[66:81]
	ds_read_b128 v[122:125], v240 offset:8192
	v_mfma_f32_32x32x16_bf16 v[98:113], v[194:197], v[146:149], v[66:81]
	ds_read_b128 v[114:117], v241
	v_mfma_f32_32x32x16_bf16 v[82:97], v[198:201], v[150:153], v[82:97]
	ds_read_b128 v[118:121], v241 offset:8192
	s_waitcnt lgkmcnt(0)
	v_mfma_f32_32x32x16_bf16 v[98:113], v[122:125], v[150:153], v[98:113]
	ds_read_b128 v[122:125], v243
	v_mfma_f32_32x32x16_bf16 v[82:97], v[114:117], v[154:157], v[82:97]
	ds_read_b128 v[114:117], v243 offset:8192
	v_mfma_f32_32x32x16_bf16 v[98:113], v[118:121], v[154:157], v[98:113]
	s_waitcnt lgkmcnt(0)
	v_mfma_f32_32x32x16_bf16 v[82:97], v[122:125], v[158:161], v[82:97]
	v_mfma_f32_32x32x16_bf16 v[98:113], v[114:117], v[158:161], v[98:113]
	s_nop 0
	ds_read_b128 v[122:125], v244 offset:53248
	ds_read_b128 v[118:121], v244 offset:57344
	ds_read_b128 v[114:117], v244 offset:61440
	s_add_i32 s26, s21, 0x80
	s_cmp_le_u32 s26, s20
	s_cbranch_scc0 .Lr2u1_Lnear_u1o

.Lr2u1_LBB0_236:
	s_waitcnt lgkmcnt(0)
	ds_read_b128 v[202:205], v239 offset:16384
	ds_read_b128 v[194:197], v239 offset:24576
	ds_read_b128 v[198:201], v240 offset:16384
	v_mfma_f32_32x32x16_bf16 v[18:33], v[118:121], v[190:193], v[18:33]
	v_exp_f32_e32 v118, v110
	v_exp_f32_e32 v119, v111
	v_add_f32_e32 v120, v122, v118
	v_add_f32_e32 v121, v123, v119
	v_cvt_pk_bf16_f32 v188, v118, v119
	v_mfma_f32_32x32x16_bf16 v[2:17], v[114:117], v[190:193], v[2:17]
	v_exp_f32_e32 v114, v112
	v_exp_f32_e32 v115, v113
	v_add_f32_e32 v116, v120, v114
	v_add_f32_e32 v117, v121, v115
	v_cvt_pk_bf16_f32 v189, v114, v115
	v_add_f32_e32 v212, v116, v117
	v_cmp_nge_f32_e32 vcc, s7, v212
	s_cbranch_vccnz .Lr2u1_Lrare_u1o

.LBB0_266:
	s_nop 6
	v_max_f32_e32 v0, v19, v19
	v_max_f32_e32 v39, v3, v3
	v_max_f32_e32 v0, v39, v0
	v_max3_f32 v0, v2, v18, v0
	v_max3_f32 v39, v20, v5, v21
	v_max3_f32 v0, v0, v4, v39
	v_max3_f32 v39, v22, v7, v23
	v_max3_f32 v0, v0, v6, v39
	v_max3_f32 v39, v24, v9, v25
	v_max3_f32 v0, v0, v8, v39
	v_max3_f32 v39, v26, v11, v27
	v_max3_f32 v0, v0, v10, v39
	v_max3_f32 v39, v28, v13, v29
	v_max3_f32 v0, v0, v12, v39
	v_max3_f32 v39, v30, v15, v31
	v_max3_f32 v0, v0, v14, v39
	v_max3_f32 v39, v32, v17, v33
	v_max3_f32 v0, v0, v16, v39
	v_mov_b32_e32 v39, v0
	s_nop 1
	v_permlane32_swap_b32_e32 v0, v39
	v_max_f32_e32 v39, v39, v39
	v_max_f32_e32 v0, v0, v0
	v_max_f32_e32 v213, v0, v39
	v_sub_f32_e32 v0, v2, v213
	v_exp_f32_e32 v40, v0
	v_sub_f32_e32 v0, v18, v213
	v_exp_f32_e32 v41, v0
	v_sub_f32_e32 v0, v3, v213
	v_sub_f32_e32 v2, v19, v213
	v_exp_f32_e32 v0, v0
	v_exp_f32_e32 v2, v2
	v_add_f32_e32 v3, v41, v40
	s_movk_i32 s27, 0x510
	v_cvt_pk_bf16_f32 v162, v40, v0
	v_pk_add_f32 v[18:19], v[2:3], v[0:1]
	v_sub_f32_e32 v3, v4, v213
	v_sub_f32_e32 v4, v20, v213
	v_pk_add_f32 v[18:19], v[18:19], v[18:19] op_sel_hi:[0,1]
	v_exp_f32_e32 v43, v4
	v_sub_f32_e32 v4, v5, v213
	v_exp_f32_e32 v3, v3
	v_exp_f32_e32 v18, v4
	v_sub_f32_e32 v4, v21, v213
	v_exp_f32_e32 v4, v4
	v_add_f32_e32 v5, v43, v3
	v_xad_u32 v0, v37, -1, v236
	v_cvt_pk_bf16_f32 v178, v41, v2
	v_pk_add_f32 v[20:21], v[4:5], v[18:19]
	v_sub_f32_e32 v5, v6, v213
	v_sub_f32_e32 v6, v22, v213
	v_pk_add_f32 v[20:21], v[20:21], v[20:21] op_sel_hi:[0,1]
	v_exp_f32_e32 v19, v6
	v_sub_f32_e32 v6, v7, v213
	v_exp_f32_e32 v5, v5
	v_exp_f32_e32 v20, v6
	v_sub_f32_e32 v6, v23, v213
	v_exp_f32_e32 v6, v6
	v_add_f32_e32 v7, v19, v5
	v_and_b32_e32 v0, 3, v0
	v_mov_b32_e32 v2, s31
	v_pk_add_f32 v[22:23], v[6:7], v[20:21]
	v_sub_f32_e32 v7, v8, v213
	v_sub_f32_e32 v8, v24, v213
	v_pk_add_f32 v[22:23], v[22:23], v[22:23] op_sel_hi:[0,1]
	v_exp_f32_e32 v21, v8
	v_sub_f32_e32 v8, v9, v213
	v_exp_f32_e32 v7, v7
	v_exp_f32_e32 v22, v8
	v_sub_f32_e32 v8, v25, v213
	v_exp_f32_e32 v8, v8
	v_add_f32_e32 v9, v21, v7
	s_add_i32 s20, s20, s56
	v_mad_u32_u24 v244, v0, s27, v2
	v_pk_add_f32 v[24:25], v[8:9], v[22:23]
	v_sub_f32_e32 v9, v10, v213
	v_sub_f32_e32 v10, v26, v213
	v_pk_add_f32 v[24:25], v[24:25], v[24:25] op_sel_hi:[0,1]
	v_exp_f32_e32 v23, v10
	v_sub_f32_e32 v10, v11, v213
	v_exp_f32_e32 v9, v9
	v_exp_f32_e32 v24, v10
	v_sub_f32_e32 v10, v27, v213
	v_exp_f32_e32 v10, v10
	v_add_f32_e32 v11, v23, v9
	v_add_u32_e32 v2, s20, v233
	v_cvt_pk_bf16_f32 v163, v3, v18
	v_pk_add_f32 v[26:27], v[10:11], v[24:25]
	v_sub_f32_e32 v11, v12, v213
	v_sub_f32_e32 v12, v28, v213
	v_pk_add_f32 v[26:27], v[26:27], v[26:27] op_sel_hi:[0,1]
	v_exp_f32_e32 v25, v12
	v_sub_f32_e32 v12, v13, v213
	v_exp_f32_e32 v11, v11
	v_exp_f32_e32 v26, v12
	v_sub_f32_e32 v12, v29, v213
	v_exp_f32_e32 v12, v12
	v_add_f32_e32 v13, v25, v11
	v_ashrrev_i32_e32 v3, 31, v2
	v_lshlrev_b64 v[2:3], 12, v[2:3]
	v_pk_add_f32 v[28:29], v[12:13], v[26:27]
	v_sub_f32_e32 v13, v14, v213
	v_sub_f32_e32 v14, v30, v213
	v_pk_add_f32 v[28:29], v[28:29], v[28:29] op_sel_hi:[0,1]
	v_exp_f32_e32 v27, v14
	v_sub_f32_e32 v14, v15, v213
	v_exp_f32_e32 v13, v13
	v_exp_f32_e32 v28, v14
	v_sub_f32_e32 v14, v31, v213
	v_exp_f32_e32 v14, v14
	v_sub_f32_e32 v15, v16, v213
	v_exp_f32_e32 v48, v15
	v_sub_f32_e32 v15, v32, v213
	v_exp_f32_e32 v32, v15
	v_add_f32_e32 v15, v27, v13
	v_pk_add_f32 v[30:31], v[14:15], v[28:29]
	v_and_b32_e32 v0, 15, v34
	v_pk_add_f32 v[30:31], v[30:31], v[30:31] op_sel_hi:[0,1]
	v_sub_f32_e32 v15, v17, v213
	v_or_b32_e32 v2, s37, v2
	v_lshlrev_b32_e32 v0, 4, v0
	s_add_i32 s21, s21, s36
	v_exp_f32_e32 v30, v15
	v_sub_f32_e32 v15, v33, v213
	v_lshl_add_u64 v[214:215], v[2:3], 0, v[0:1]
	v_add_u32_e32 v2, s21, v36
	v_and_b32_e32 v39, 7, v38
	v_bitop3_b32 v44, v38, v234, 7 bitop3:0x6c
	v_exp_f32_e32 v38, v15
	v_ashrrev_i32_e32 v3, 31, v2
	v_lshlrev_b64 v[2:3], 15, v[2:3]
	v_and_b32_e32 v0, 7, v35
	s_and_b32 s26, s47, 15
	v_lshl_or_b32 v2, v0, 4, v2
	v_sub_u32_e32 v0, v236, v235
	v_lshlrev_b32_e32 v42, 7, v235
	v_bitop3_b32 v45, v234, v39, 2 bitop3:0x36
	v_bitop3_b32 v46, v234, v39, 4 bitop3:0x36
	v_bitop3_b32 v47, v234, v39, 6 bitop3:0x36
	s_lshl_b32 s26, s26, 7
	v_add_f32_e32 v39, v32, v48
	v_cvt_pk_bf16_f32 v188, v27, v14
	v_subrev_u32_e32 v0, s28, v0
	v_mov_b32_e32 v14, v1
	v_mov_b32_e32 v15, v1
	s_lshl_b32 s17, s46, 1
	s_lshr_b32 s19, s16, 6
	v_pk_add_f32 v[16:17], v[38:39], v[30:31]
	v_cvt_pk_bf16_f32 v164, v5, v20
	v_cvt_pk_bf16_f32 v165, v7, v22
	v_cvt_pk_bf16_f32 v170, v9, v24
	v_cvt_pk_bf16_f32 v171, v11, v26
	v_cvt_pk_bf16_f32 v172, v13, v28
	v_cvt_pk_bf16_f32 v173, v48, v30
	v_cvt_pk_bf16_f32 v179, v43, v4
	v_cvt_pk_bf16_f32 v180, v19, v6
	v_cvt_pk_bf16_f32 v181, v21, v8
	v_cvt_pk_bf16_f32 v186, v23, v10
	v_cvt_pk_bf16_f32 v187, v25, v12
	v_cvt_pk_bf16_f32 v189, v32, v38
	v_lshl_or_b32 v245, v44, 4, v42
	v_lshl_or_b32 v246, v45, 4, v42
	v_lshl_or_b32 v247, v46, 4, v42
	v_lshl_or_b32 v248, v47, 4, v42
	v_lshl_add_u64 v[216:217], v[2:3], 0, s[44:45]
	v_subrev_u32_e32 v249, s26, v0
	v_mov_b32_e32 v0, v1
	v_mov_b32_e32 v2, v1
	v_mov_b32_e32 v3, v1
	v_mov_b32_e32 v4, v1
	v_mov_b32_e32 v5, v1
	v_mov_b32_e32 v6, v1
	v_mov_b32_e32 v7, v1
	v_mov_b32_e32 v8, v1
	v_mov_b32_e32 v9, v1
	v_mov_b32_e32 v10, v1
	v_mov_b32_e32 v11, v1
	v_mov_b32_e32 v12, v1
	v_mov_b32_e32 v13, v1
	v_mov_b64_e32 v[64:65], v[14:15]
	v_mov_b64_e32 v[48:49], v[14:15]
	v_mov_b64_e32 v[32:33], v[14:15]
	s_add_i32 s18, s17, 2
	s_add_i32 s19, s19, 1
	v_xor_b32_e32 v66, 0x80000000, v213
	v_add_f32_e32 v243, v16, v17
	v_mov_b64_e32 v[62:63], v[12:13]
	v_mov_b64_e32 v[60:61], v[10:11]
	v_mov_b64_e32 v[58:59], v[8:9]
	v_mov_b64_e32 v[56:57], v[6:7]
	v_mov_b64_e32 v[54:55], v[4:5]
	v_mov_b64_e32 v[52:53], v[2:3]
	v_mov_b64_e32 v[50:51], v[0:1]
	v_mov_b64_e32 v[46:47], v[12:13]
	v_mov_b64_e32 v[44:45], v[10:11]
	v_mov_b64_e32 v[42:43], v[8:9]
	v_mov_b64_e32 v[40:41], v[6:7]
	v_mov_b64_e32 v[38:39], v[4:5]
	v_mov_b64_e32 v[36:37], v[2:3]
	v_mov_b64_e32 v[34:35], v[0:1]
	v_mov_b64_e32 v[30:31], v[12:13]
	v_mov_b64_e32 v[28:29], v[10:11]
	v_mov_b64_e32 v[26:27], v[8:9]
	v_mov_b64_e32 v[24:25], v[6:7]
	v_mov_b64_e32 v[22:23], v[4:5]
	v_mov_b64_e32 v[20:21], v[2:3]
	v_mov_b64_e32 v[18:19], v[0:1]
	v_mov_b64_e32 v[16:17], v[14:15]
	s_mov_b32 s22, 1
	s_mov_b32 s23, 0x8000
	s_min_u32 s19, s18, s19
	v_mov_b32_e32 v67, v66
	v_mov_b32_e32 v68, v66
	v_mov_b32_e32 v69, v66
	v_mov_b32_e32 v70, v66
	v_mov_b32_e32 v71, v66
	v_mov_b32_e32 v72, v66
	v_mov_b32_e32 v73, v66
	v_mov_b32_e32 v74, v66
	v_mov_b32_e32 v75, v66
	v_mov_b32_e32 v76, v66
	v_mov_b32_e32 v77, v66
	v_mov_b32_e32 v78, v66
	v_mov_b32_e32 v79, v66
	v_mov_b32_e32 v80, v66
	v_mov_b32_e32 v81, v66
	s_mov_b32 s28, 0
	s_movk_i32 s20, 0xf0
	v_mov_b32_e32 v166, 0
	v_mov_b32_e32 v167, 0
	v_mov_b32_e32 v168, 0
	v_mov_b32_e32 v169, 0
	v_mov_b32_e32 v174, 0
	v_mov_b32_e32 v175, 0
	v_mov_b32_e32 v176, 0
	v_mov_b32_e32 v177, 0
	v_mov_b32_e32 v182, 0
	v_mov_b32_e32 v183, 0
	v_mov_b32_e32 v184, 0
	v_mov_b32_e32 v185, 0
	v_mov_b32_e32 v190, 0
	v_mov_b32_e32 v191, 0
	v_mov_b32_e32 v192, 0
	v_mov_b32_e32 v193, 0
	v_mov_b64_e32 v[14:15], v[12:13]
	v_mov_b64_e32 v[12:13], v[10:11]
	v_mov_b64_e32 v[10:11], v[8:9]
	v_mov_b64_e32 v[8:9], v[6:7]
	v_mov_b64_e32 v[6:7], v[4:5]
	v_mov_b64_e32 v[4:5], v[2:3]
	v_mov_b64_e32 v[2:3], v[0:1]
	s_mov_b32 s31, 0x4000
	s_mov_b32 s33, 0
	v_add_u32_e32 v245, 0x8000, v245
	v_add_u32_e32 v246, 0x8000, v246
	v_add_u32_e32 v247, 0x8000, v247
	v_add_u32_e32 v248, 0x8000, v248
	ds_read_b128 v[202:205], v239 offset:16384
	ds_read_b128 v[194:197], v239 offset:24576
	ds_read_b128 v[198:201], v240 offset:16384

.LBB0_288:
	ds_read_b128 v[126:129], v245 offset:16384
	s_waitcnt lgkmcnt(1)
	v_mfma_f32_32x32x16_bf16 v[82:97], v[202:205], v[146:149], v[66:81]
	ds_read_b128 v[122:125], v240 offset:24576
	v_mfma_f32_32x32x16_bf16 v[98:113], v[194:197], v[146:149], v[66:81]
	ds_read_b128 v[114:117], v241 offset:16384
	v_mfma_f32_32x32x16_bf16 v[82:97], v[198:201], v[150:153], v[82:97]
	ds_read_b128 v[118:121], v241 offset:24576
	s_waitcnt lgkmcnt(0)
	v_mfma_f32_32x32x16_bf16 v[98:113], v[122:125], v[150:153], v[98:113]
	ds_read_b128 v[122:125], v242 offset:16384
	v_mfma_f32_32x32x16_bf16 v[82:97], v[114:117], v[154:157], v[82:97]
	ds_read_b128 v[114:117], v242 offset:24576
	v_mfma_f32_32x32x16_bf16 v[98:113], v[118:121], v[154:157], v[98:113]
	s_waitcnt lgkmcnt(0)
	v_mfma_f32_32x32x16_bf16 v[82:97], v[122:125], v[158:161], v[82:97]
	v_mfma_f32_32x32x16_bf16 v[98:113], v[114:117], v[158:161], v[98:113]
	s_nop 0
	ds_read_b128 v[122:125], v245 offset:20480
	ds_read_b128 v[118:121], v245 offset:24576
	ds_read_b128 v[114:117], v245 offset:28672
	s_cmp_le_u32 s20, s16
	s_cbranch_scc0 .Lnear_u2e

.LBB0_299:
	s_waitcnt lgkmcnt(0)
	ds_read_b128 v[202:205], v239 offset:32768
	ds_read_b128 v[194:197], v239 offset:40960
	ds_read_b128 v[198:201], v240 offset:32768
	v_mfma_f32_32x32x16_bf16 v[18:33], v[118:121], v[186:189], v[18:33]
	v_exp_f32_e32 v118, v110
	v_exp_f32_e32 v119, v111
	v_add_f32_e32 v0, v0, v118
	v_add_f32_e32 v120, v122, v119
	v_cvt_pk_bf16_f32 v192, v118, v119
	v_mfma_f32_32x32x16_bf16 v[2:17], v[114:117], v[186:189], v[2:17]
	v_exp_f32_e32 v114, v112
	v_exp_f32_e32 v115, v113
	v_add_f32_e32 v0, v0, v114
	v_add_f32_e32 v116, v120, v115
	v_cvt_pk_bf16_f32 v193, v114, v115
	v_add_f32_e32 v212, v0, v116
	v_cmp_nge_f32_e32 vcc, s7, v212
	s_cbranch_vccnz .Lrare_u2e

.LBB0_328:
	ds_read_b128 v[126:129], v245 offset:32768
	s_waitcnt lgkmcnt(1)
	v_mfma_f32_32x32x16_bf16 v[82:97], v[202:205], v[146:149], v[66:81]
	ds_read_b128 v[122:125], v240 offset:40960
	v_mfma_f32_32x32x16_bf16 v[98:113], v[194:197], v[146:149], v[66:81]
	ds_read_b128 v[114:117], v241 offset:32768
	v_mfma_f32_32x32x16_bf16 v[82:97], v[198:201], v[150:153], v[82:97]
	ds_read_b128 v[118:121], v241 offset:40960
	s_waitcnt lgkmcnt(0)
	v_mfma_f32_32x32x16_bf16 v[98:113], v[122:125], v[150:153], v[98:113]
	ds_read_b128 v[122:125], v242 offset:32768
	v_mfma_f32_32x32x16_bf16 v[82:97], v[114:117], v[154:157], v[82:97]
	ds_read_b128 v[114:117], v242 offset:40960
	v_mfma_f32_32x32x16_bf16 v[98:113], v[118:121], v[154:157], v[98:113]
	s_waitcnt lgkmcnt(0)
	v_mfma_f32_32x32x16_bf16 v[82:97], v[122:125], v[158:161], v[82:97]
	v_mfma_f32_32x32x16_bf16 v[98:113], v[114:117], v[158:161], v[98:113]
	s_nop 0
	ds_read_b128 v[122:125], v245 offset:36864
	ds_read_b128 v[118:121], v245 offset:40960
	ds_read_b128 v[114:117], v245 offset:45056
	s_add_i32 s26, s20, 64
	s_cmp_le_u32 s26, s16
	s_cbranch_scc0 .Lnear_u2o

.LBB0_339:
	s_waitcnt lgkmcnt(0)
	ds_read_b128 v[202:205], v239
	ds_read_b128 v[194:197], v239 offset:8192
	ds_read_b128 v[198:201], v240
	v_mfma_f32_32x32x16_bf16 v[18:33], v[118:121], v[190:193], v[18:33]
	v_exp_f32_e32 v118, v110
	v_exp_f32_e32 v119, v111
	v_add_f32_e32 v0, v0, v118
	v_add_f32_e32 v120, v122, v119
	v_cvt_pk_bf16_f32 v188, v118, v119
	v_mfma_f32_32x32x16_bf16 v[2:17], v[114:117], v[190:193], v[2:17]
	v_exp_f32_e32 v114, v112
	v_exp_f32_e32 v115, v113
	v_add_f32_e32 v0, v0, v114
	v_add_f32_e32 v116, v120, v115
	v_cvt_pk_bf16_f32 v189, v114, v115
	v_add_f32_e32 v212, v0, v116
	v_cmp_nge_f32_e32 vcc, s7, v212
	s_cbranch_vccnz .Lrare_u2o

.Lr1u2_LBB0_288:
	ds_read_b128 v[126:129], v245 offset:49152
	s_waitcnt lgkmcnt(1)
	v_mfma_f32_32x32x16_bf16 v[82:97], v[202:205], v[146:149], v[66:81]
	ds_read_b128 v[122:125], v240 offset:8192
	v_mfma_f32_32x32x16_bf16 v[98:113], v[194:197], v[146:149], v[66:81]
	ds_read_b128 v[114:117], v241
	v_mfma_f32_32x32x16_bf16 v[82:97], v[198:201], v[150:153], v[82:97]
	ds_read_b128 v[118:121], v241 offset:8192
	s_waitcnt lgkmcnt(0)
	v_mfma_f32_32x32x16_bf16 v[98:113], v[122:125], v[150:153], v[98:113]
	ds_read_b128 v[122:125], v242
	v_mfma_f32_32x32x16_bf16 v[82:97], v[114:117], v[154:157], v[82:97]
	ds_read_b128 v[114:117], v242 offset:8192
	v_mfma_f32_32x32x16_bf16 v[98:113], v[118:121], v[154:157], v[98:113]
	s_waitcnt lgkmcnt(0)
	v_mfma_f32_32x32x16_bf16 v[82:97], v[122:125], v[158:161], v[82:97]
	v_mfma_f32_32x32x16_bf16 v[98:113], v[114:117], v[158:161], v[98:113]
	s_nop 0
	ds_read_b128 v[122:125], v245 offset:53248
	ds_read_b128 v[118:121], v245 offset:57344
	ds_read_b128 v[114:117], v245 offset:61440
	s_cmp_le_u32 s20, s16
	s_cbranch_scc0 .Lr1u2_Lnear_u2e

.Lr1u2_LBB0_299:
	s_waitcnt lgkmcnt(0)
	ds_read_b128 v[202:205], v239 offset:16384
	ds_read_b128 v[194:197], v239 offset:24576
	ds_read_b128 v[198:201], v240 offset:16384
	v_mfma_f32_32x32x16_bf16 v[18:33], v[118:121], v[186:189], v[18:33]
	v_exp_f32_e32 v118, v110
	v_exp_f32_e32 v119, v111
	v_add_f32_e32 v0, v0, v118
	v_add_f32_e32 v120, v122, v119
	v_cvt_pk_bf16_f32 v192, v118, v119
	v_mfma_f32_32x32x16_bf16 v[2:17], v[114:117], v[186:189], v[2:17]
	v_exp_f32_e32 v114, v112
	v_exp_f32_e32 v115, v113
	v_add_f32_e32 v0, v0, v114
	v_add_f32_e32 v116, v120, v115
	v_cvt_pk_bf16_f32 v193, v114, v115
	v_add_f32_e32 v212, v0, v116
	v_cmp_nge_f32_e32 vcc, s7, v212
	s_cbranch_vccnz .Lr1u2_Lrare_u2e

.Lr1u2_LBB0_328:
	ds_read_b128 v[126:129], v245 offset:16384
	s_waitcnt lgkmcnt(1)
	v_mfma_f32_32x32x16_bf16 v[82:97], v[202:205], v[146:149], v[66:81]
	ds_read_b128 v[122:125], v240 offset:24576
	v_mfma_f32_32x32x16_bf16 v[98:113], v[194:197], v[146:149], v[66:81]
	ds_read_b128 v[114:117], v241 offset:16384
	v_mfma_f32_32x32x16_bf16 v[82:97], v[198:201], v[150:153], v[82:97]
	ds_read_b128 v[118:121], v241 offset:24576
	s_waitcnt lgkmcnt(0)
	v_mfma_f32_32x32x16_bf16 v[98:113], v[122:125], v[150:153], v[98:113]
	ds_read_b128 v[122:125], v242 offset:16384
	v_mfma_f32_32x32x16_bf16 v[82:97], v[114:117], v[154:157], v[82:97]
	ds_read_b128 v[114:117], v242 offset:24576
	v_mfma_f32_32x32x16_bf16 v[98:113], v[118:121], v[154:157], v[98:113]
	s_waitcnt lgkmcnt(0)
	v_mfma_f32_32x32x16_bf16 v[82:97], v[122:125], v[158:161], v[82:97]
	v_mfma_f32_32x32x16_bf16 v[98:113], v[114:117], v[158:161], v[98:113]
	s_nop 0
	ds_read_b128 v[122:125], v245 offset:20480
	ds_read_b128 v[118:121], v245 offset:24576
	ds_read_b128 v[114:117], v245 offset:28672
	s_add_i32 s26, s20, 64
	s_cmp_le_u32 s26, s16
	s_cbranch_scc0 .Lr1u2_Lnear_u2o

.Lr1u2_LBB0_339:
	s_waitcnt lgkmcnt(0)
	ds_read_b128 v[202:205], v239 offset:32768
	ds_read_b128 v[194:197], v239 offset:40960
	ds_read_b128 v[198:201], v240 offset:32768
	v_mfma_f32_32x32x16_bf16 v[18:33], v[118:121], v[190:193], v[18:33]
	v_exp_f32_e32 v118, v110
	v_exp_f32_e32 v119, v111
	v_add_f32_e32 v0, v0, v118
	v_add_f32_e32 v120, v122, v119
	v_cvt_pk_bf16_f32 v188, v118, v119
	v_mfma_f32_32x32x16_bf16 v[2:17], v[114:117], v[190:193], v[2:17]
	v_exp_f32_e32 v114, v112
	v_exp_f32_e32 v115, v113
	v_add_f32_e32 v0, v0, v114
	v_add_f32_e32 v116, v120, v115
	v_cvt_pk_bf16_f32 v189, v114, v115
	v_add_f32_e32 v212, v0, v116
	v_cmp_nge_f32_e32 vcc, s7, v212
	s_cbranch_vccnz .Lr1u2_Lrare_u2o

.Lr2u2_LBB0_288:
	ds_read_b128 v[126:129], v245 offset:32768
	s_waitcnt lgkmcnt(1)
	v_mfma_f32_32x32x16_bf16 v[82:97], v[202:205], v[146:149], v[66:81]
	ds_read_b128 v[122:125], v240 offset:40960
	v_mfma_f32_32x32x16_bf16 v[98:113], v[194:197], v[146:149], v[66:81]
	ds_read_b128 v[114:117], v241 offset:32768
	v_mfma_f32_32x32x16_bf16 v[82:97], v[198:201], v[150:153], v[82:97]
	ds_read_b128 v[118:121], v241 offset:40960
	s_waitcnt lgkmcnt(0)
	v_mfma_f32_32x32x16_bf16 v[98:113], v[122:125], v[150:153], v[98:113]
	ds_read_b128 v[122:125], v242 offset:32768
	v_mfma_f32_32x32x16_bf16 v[82:97], v[114:117], v[154:157], v[82:97]
	ds_read_b128 v[114:117], v242 offset:40960
	v_mfma_f32_32x32x16_bf16 v[98:113], v[118:121], v[154:157], v[98:113]
	s_waitcnt lgkmcnt(0)
	v_mfma_f32_32x32x16_bf16 v[82:97], v[122:125], v[158:161], v[82:97]
	v_mfma_f32_32x32x16_bf16 v[98:113], v[114:117], v[158:161], v[98:113]
	s_nop 0
	ds_read_b128 v[122:125], v245 offset:36864
	ds_read_b128 v[118:121], v245 offset:40960
	ds_read_b128 v[114:117], v245 offset:45056
	s_cmp_le_u32 s20, s16
	s_cbranch_scc0 .Lr2u2_Lnear_u2e

.Lr2u2_LBB0_299:
	s_waitcnt lgkmcnt(0)
	ds_read_b128 v[202:205], v239
	ds_read_b128 v[194:197], v239 offset:8192
	ds_read_b128 v[198:201], v240
	v_mfma_f32_32x32x16_bf16 v[18:33], v[118:121], v[186:189], v[18:33]
	v_exp_f32_e32 v118, v110
	v_exp_f32_e32 v119, v111
	v_add_f32_e32 v0, v0, v118
	v_add_f32_e32 v120, v122, v119
	v_cvt_pk_bf16_f32 v192, v118, v119
	v_mfma_f32_32x32x16_bf16 v[2:17], v[114:117], v[186:189], v[2:17]
	v_exp_f32_e32 v114, v112
	v_exp_f32_e32 v115, v113
	v_add_f32_e32 v0, v0, v114
	v_add_f32_e32 v116, v120, v115
	v_cvt_pk_bf16_f32 v193, v114, v115
	v_add_f32_e32 v212, v0, v116
	v_cmp_nge_f32_e32 vcc, s7, v212
	s_cbranch_vccnz .Lr2u2_Lrare_u2e

.Lr2u2_LBB0_328:
	ds_read_b128 v[126:129], v245 offset:49152
	s_waitcnt lgkmcnt(1)
	v_mfma_f32_32x32x16_bf16 v[82:97], v[202:205], v[146:149], v[66:81]
	ds_read_b128 v[122:125], v240 offset:8192
	v_mfma_f32_32x32x16_bf16 v[98:113], v[194:197], v[146:149], v[66:81]
	ds_read_b128 v[114:117], v241
	v_mfma_f32_32x32x16_bf16 v[82:97], v[198:201], v[150:153], v[82:97]
	ds_read_b128 v[118:121], v241 offset:8192
	s_waitcnt lgkmcnt(0)
	v_mfma_f32_32x32x16_bf16 v[98:113], v[122:125], v[150:153], v[98:113]
	ds_read_b128 v[122:125], v242
	v_mfma_f32_32x32x16_bf16 v[82:97], v[114:117], v[154:157], v[82:97]
	ds_read_b128 v[114:117], v242 offset:8192
	v_mfma_f32_32x32x16_bf16 v[98:113], v[118:121], v[154:157], v[98:113]
	s_waitcnt lgkmcnt(0)
	v_mfma_f32_32x32x16_bf16 v[82:97], v[122:125], v[158:161], v[82:97]
	v_mfma_f32_32x32x16_bf16 v[98:113], v[114:117], v[158:161], v[98:113]
	s_nop 0
	ds_read_b128 v[122:125], v245 offset:53248
	ds_read_b128 v[118:121], v245 offset:57344
	ds_read_b128 v[114:117], v245 offset:61440
	s_add_i32 s26, s20, 64
	s_cmp_le_u32 s26, s16
	s_cbranch_scc0 .Lr2u2_Lnear_u2o

.Lr2u2_LBB0_339:
	s_waitcnt lgkmcnt(0)
	ds_read_b128 v[202:205], v239 offset:16384
	ds_read_b128 v[194:197], v239 offset:24576
	ds_read_b128 v[198:201], v240 offset:16384
	v_mfma_f32_32x32x16_bf16 v[18:33], v[118:121], v[190:193], v[18:33]
	v_exp_f32_e32 v118, v110
	v_exp_f32_e32 v119, v111
	v_add_f32_e32 v0, v0, v118
	v_add_f32_e32 v120, v122, v119
	v_cvt_pk_bf16_f32 v188, v118, v119
	v_mfma_f32_32x32x16_bf16 v[2:17], v[114:117], v[190:193], v[2:17]
	v_exp_f32_e32 v114, v112
	v_exp_f32_e32 v115, v113
	v_add_f32_e32 v0, v0, v114
	v_add_f32_e32 v116, v120, v115
	v_cvt_pk_bf16_f32 v189, v114, v115
	v_add_f32_e32 v212, v0, v116
	v_cmp_nge_f32_e32 vcc, s7, v212
	s_cbranch_vccnz .Lr2u2_Lrare_u2o
